# v72 + last row-sum adds of each softmax block interleaved with the independent bf16 converts (no back-to-back dependent VALU chain)
# baseline (speedup 1.0000x reference)
; #define SBAR() __builtin_amdgcn_sched_barrier(0)
; #define ATT_DMA_K(t) do { const bf16_t* kg_ = Kh + (size_t)(t) * 64 * LDK; LAS unsigned char* sb_ = lds + ((t) & 3) * KBUF; \
;     _Pragma("unroll") for (int i_ = 0; i_ < NKP; ++i_) __builtin_amdgcn_global_load_lds((const unsigned*)(kg_ + kgo[i_]), (LAS unsigned*)(sb_ + (wid + 8 * i_) * 1024), 16, 0, 0); } while (0)
; #define ATT_DMA_V(t, vs) do { const bf16_t* vg_ = Vh + (size_t)(t) * 64 * LDV; LAS unsigned char* sb_ = lds + V_OFF + (vs) * SHM_V; \
;     _Pragma("unroll") for (int i_ = 0; i_ < 2; ++i_) __builtin_amdgcn_global_load_lds((const unsigned*)(vg_ + vgo[i_]), (LAS unsigned*)(sb_ + (2 * wid + i_) * 1024), 16, 0, 0); } while (0)
; #define ATT_SEG(t) do { if constexpr (MODE != 0) { if (((t) == tL && tL > 0) || (t) == tR) { const float f_ = (t) == tR ? fR : fL; l_reg *= f_; \
;     _Pragma("unroll") for (int d = 0; d < 4; ++d) _Pragma("unroll") for (int r = 0; r < 16; ++r) o[d][r] *= f_; } } } while (0)
; #define ATT_TOP(N) do { asm volatile("s_waitcnt vmcnt(%0)" :: "n"(N) : "memory"); __builtin_amdgcn_s_barrier(); asm volatile("" ::: "memory"); } while (0)
; DI void expsum(f32x16& p, float& l_reg, bf16x8& pa0, bf16x8& pa1) {
; #pragma unroll
;     for (int r = 0; r < 16; ++r) p[r] = __builtin_amdgcn_exp2f(p[r]);
;     float ps = 0.f;
; #pragma unroll
;     for (int r = 0; r < 16; ++r) ps += p[r];
;     l_reg += ps; asm volatile("" : "+v"(l_reg));
;     ...
;     ATT_PK4(p, 0, pa0); ATT_PK4(p, 8, pa1);
;     ...
; }
; template <int DQK, int MODE, int LDQ, int LDK, int LDV> ...
;     ...
;     f32x16 pA, pB; bf16x8 pa0, pa1;
;     int v0 = 0, v1 = 1, v2 = 2;
;     ATT_TOP(NKP + 2);
;     { bf16x8 kf[NDA]; k_reads<DQK, 0, NDA>(kf, lds, 0, r32, hi); ATT_LGKM0(); qk_mma<0, NDA>(pA, kf, qr);
;       if constexpr (ND0 > NDA) { bf16x8 kg[ND0 - NDA]; k_reads<DQK, NDA, ND0>(kg, lds, 0, r32, hi); ATT_LGKM0(); qk_mma<NDA, ND0>(pA, kg, qr); }
;       ATT_BIAS(pA, 0, 0); }
;     if (wid >= 4) __builtin_amdgcn_s_setprio(1);
;     for (int j = 0; j < NT; ++j) {
;         if (j + 2 < NT) ATT_TOP(NKP + 2); else ATT_TOP(0);
;         if (j + 3 < NT) ATT_DMA_K(j + 3);
;         if (j + 2 < NT) ATT_DMA_V(j + 2, v2);
;         ATT_SEG(j); SBAR();
;         ATT_STEP(pA, pB, 0, v0, true, 1, j);
;         ATT_STEP(pB, pA, 1, v0, (j + 1 < NT), 0, j + 1);
.Lhw_d0_b_n1922:
	ds_read_b128 v[122:125], v196 offset:4096
	ds_read_b128 v[132:135], v197 offset:4096
	s_lshl_b32 s2, s1, 14
	ds_read_b128 v[136:139], v198 offset:4096
	ds_read_b128 v[140:143], v199 offset:4096
	v_add_u32_e32 v121, s2, v106
	ds_read_b64_tr_b16 v[144:145], v121 offset:0
	ds_read_b64_tr_b16 v[146:147], v121 offset:0x800
	ds_read_b64_tr_b16 v[148:149], v121 offset:0x1000
	ds_read_b64_tr_b16 v[150:151], v121 offset:0x1800
	ds_read_b64_tr_b16 v[152:153], v121 offset:0x200
	ds_read_b64_tr_b16 v[154:155], v121 offset:0xa00
	ds_read_b64_tr_b16 v[156:157], v121 offset:0x1200
	ds_read_b64_tr_b16 v[158:159], v121 offset:0x1a00
	ds_read_b64_tr_b16 v[162:163], v121 offset:0x400
	ds_read_b64_tr_b16 v[164:165], v121 offset:0xc00
	ds_read_b64_tr_b16 v[166:167], v121 offset:0x1400
	ds_read_b64_tr_b16 v[168:169], v121 offset:0x1c00
	ds_read_b64_tr_b16 v[170:171], v121 offset:0x600
	ds_read_b64_tr_b16 v[172:173], v121 offset:0xe00
	ds_read_b64_tr_b16 v[174:175], v121 offset:0x1600
	ds_read_b64_tr_b16 v[176:177], v121 offset:0x1e00
	s_setprio 2
	v_exp_f32_e32 v64, v64
	v_exp_f32_e32 v65, v65
	v_exp_f32_e32 v66, v66
	v_exp_f32_e32 v67, v67
	v_exp_f32_e32 v68, v68
	v_exp_f32_e32 v69, v69
	v_add_f32_e32 v126, v65, v64
	v_exp_f32_e32 v70, v70
	v_add_f32_e32 v126, v66, v126
	v_exp_f32_e32 v71, v71
	v_add_f32_e32 v126, v67, v126
	v_exp_f32_e32 v72, v72
	v_add_f32_e32 v126, v68, v126
	v_exp_f32_e32 v73, v73
	v_add_f32_e32 v126, v69, v126
	v_exp_f32_e32 v74, v74
	v_add_f32_e32 v126, v70, v126
	v_exp_f32_e32 v75, v75
	v_add_f32_e32 v126, v71, v126
	v_exp_f32_e32 v76, v76
	v_add_f32_e32 v126, v72, v126
	v_exp_f32_e32 v77, v77
	v_add_f32_e32 v126, v73, v126
	v_exp_f32_e32 v78, v78
	v_add_f32_e32 v126, v74, v126
	v_exp_f32_e32 v79, v79
	v_add_f32_e32 v126, v75, v126
	v_cvt_pk_bf16_f32 v64, v64, v65
	v_add_f32_e32 v126, v76, v126
	v_cvt_pk_bf16_f32 v65, v66, v67
	v_add_f32_e32 v126, v77, v126
	v_cvt_pk_bf16_f32 v66, v68, v69
	v_add_f32_e32 v126, v78, v126
	v_cvt_pk_bf16_f32 v67, v70, v71
	v_add_f32_e32 v126, v79, v126
	v_cvt_pk_bf16_f32 v68, v72, v73
	v_add_f32_e32 v120, v126, v120
	v_cvt_pk_bf16_f32 v69, v74, v75
	v_cvt_pk_bf16_f32 v70, v76, v77
	v_cvt_pk_bf16_f32 v71, v78, v79
	s_waitcnt lgkmcnt(0)
	s_setprio 1
	v_mfma_f32_32x32x16_bf16 v[0:15], v[64:67], v[144:147], v[0:15]
	s_sub_i32 s3, s0, s98
	s_cmp_lt_u32 s3, s100
	v_mfma_f32_32x32x16_bf16 v[48:63], v[64:67], v[152:155], v[48:63]
	v_mfma_f32_32x32x16_bf16 v[32:47], v[64:67], v[162:165], v[32:47]
	v_mfma_f32_32x32x16_bf16 v[16:31], v[64:67], v[170:173], v[16:31]
	v_mfma_f32_32x32x16_bf16 v[0:15], v[68:71], v[148:151], v[0:15]
	v_mfma_f32_32x32x16_bf16 v[48:63], v[68:71], v[156:159], v[48:63]
	v_mfma_f32_32x32x16_bf16 v[32:47], v[68:71], v[166:169], v[32:47]
	v_mfma_f32_32x32x16_bf16 v[16:31], v[68:71], v[174:177], v[16:31]
	v_mfma_f32_32x32x16_bf16 v[64:79], v[122:125], v[92:95], 0
	v_mfma_f32_32x32x16_bf16 v[64:79], v[132:135], v[88:91], v[64:79]
	v_mfma_f32_32x32x16_bf16 v[64:79], v[136:139], v[84:87], v[64:79]
	v_mfma_f32_32x32x16_bf16 v[64:79], v[140:143], v[80:83], v[64:79]
	s_setprio 0
	s_cbranch_scc1 .Lhw_d0_b_dtd0bias1
.Lhw_d0_b_n1924:
	s_add_i32 s3, s22, 0xffffc000
	s_and_b32 s3, s3, 0x6000
	v_add_u32_e32 v196, s3, v107
	v_add_u32_e32 v197, s3, v108
	v_add_u32_e32 v198, s3, v109
	v_add_u32_e32 v199, s3, v110
	ds_read_b128 v[124:127], v196
	ds_read_b128 v[132:135], v197
	ds_read_b128 v[136:139], v198
	ds_read_b128 v[140:143], v199
	ds_read_b64_tr_b16 v[144:145], v121 offset:0x2000
	ds_read_b64_tr_b16 v[146:147], v121 offset:0x2800
	ds_read_b64_tr_b16 v[148:149], v121 offset:0x3000
	ds_read_b64_tr_b16 v[150:151], v121 offset:0x3800
	ds_read_b64_tr_b16 v[152:153], v121 offset:0x2200
	ds_read_b64_tr_b16 v[154:155], v121 offset:0x2a00
	ds_read_b64_tr_b16 v[156:157], v121 offset:0x3200
	ds_read_b64_tr_b16 v[158:159], v121 offset:0x3a00
	ds_read_b64_tr_b16 v[162:163], v121 offset:0x2400
	ds_read_b64_tr_b16 v[164:165], v121 offset:0x2c00
	ds_read_b64_tr_b16 v[166:167], v121 offset:0x3400
	ds_read_b64_tr_b16 v[168:169], v121 offset:0x3c00
	ds_read_b64_tr_b16 v[170:171], v121 offset:0x2600
	ds_read_b64_tr_b16 v[172:173], v121 offset:0x2e00
	ds_read_b64_tr_b16 v[174:175], v121 offset:0x3600
	ds_read_b64_tr_b16 v[176:177], v121 offset:0x3e00
	s_setprio 2
	v_exp_f32_e32 v64, v64
	v_exp_f32_e32 v65, v65
	v_exp_f32_e32 v66, v66
	v_exp_f32_e32 v67, v67
	v_exp_f32_e32 v68, v68
	v_exp_f32_e32 v69, v69
	v_add_f32_e32 v121, v65, v64
	v_exp_f32_e32 v70, v70
	v_add_f32_e32 v121, v66, v121
	v_exp_f32_e32 v71, v71
	v_add_f32_e32 v121, v67, v121
	v_exp_f32_e32 v72, v72
	v_add_f32_e32 v121, v68, v121
	v_exp_f32_e32 v73, v73
	v_add_f32_e32 v121, v69, v121
	v_exp_f32_e32 v74, v74
	v_add_f32_e32 v121, v70, v121
	v_exp_f32_e32 v75, v75
	v_add_f32_e32 v121, v71, v121
	v_exp_f32_e32 v76, v76
	v_add_f32_e32 v121, v72, v121
	v_exp_f32_e32 v77, v77
	v_add_f32_e32 v121, v73, v121
	v_exp_f32_e32 v78, v78
	v_add_f32_e32 v121, v74, v121
	v_exp_f32_e32 v79, v79
	v_add_f32_e32 v121, v75, v121
	v_cvt_pk_bf16_f32 v64, v64, v65
	v_add_f32_e32 v121, v76, v121
	v_cvt_pk_bf16_f32 v65, v66, v67
	v_add_f32_e32 v121, v77, v121
	v_cvt_pk_bf16_f32 v66, v68, v69
	v_add_f32_e32 v121, v78, v121
	v_cvt_pk_bf16_f32 v67, v70, v71
	v_add_f32_e32 v121, v79, v121
	v_cvt_pk_bf16_f32 v68, v72, v73
	v_add_f32_e32 v120, v120, v121
	v_cvt_pk_bf16_f32 v69, v74, v75
	v_cvt_pk_bf16_f32 v70, v76, v77
	v_cvt_pk_bf16_f32 v71, v78, v79
	s_waitcnt lgkmcnt(0)
	s_setprio 1
	s_waitcnt vmcnt(3)
	s_barrier
	v_mfma_f32_32x32x16_bf16 v[0:15], v[64:67], v[144:147], v[0:15]
	s_sub_i32 s74, s0, s55
	s_cmp_lt_u32 s74, s100
	v_mfma_f32_32x32x16_bf16 v[48:63], v[64:67], v[152:155], v[48:63]
	v_mfma_f32_32x32x16_bf16 v[32:47], v[64:67], v[162:165], v[32:47]
	v_mfma_f32_32x32x16_bf16 v[16:31], v[64:67], v[170:173], v[16:31]
	v_mfma_f32_32x32x16_bf16 v[0:15], v[68:71], v[148:151], v[0:15]
	v_mfma_f32_32x32x16_bf16 v[48:63], v[68:71], v[156:159], v[48:63]
	v_mfma_f32_32x32x16_bf16 v[32:47], v[68:71], v[166:169], v[32:47]
	v_mfma_f32_32x32x16_bf16 v[16:31], v[68:71], v[174:177], v[16:31]
	v_mfma_f32_32x32x16_bf16 v[64:79], v[124:127], v[92:95], 0
	v_mfma_f32_32x32x16_bf16 v[64:79], v[132:135], v[88:91], v[64:79]
	v_mfma_f32_32x32x16_bf16 v[64:79], v[136:139], v[84:87], v[64:79]
	v_mfma_f32_32x32x16_bf16 v[64:79], v[140:143], v[80:83], v[64:79]
	s_cbranch_scc1 .Lhw_d0_b_dtd0bias2

; DI void expsum(f32x16& p, float& l_reg, bf16x8& pa0, bf16x8& pa1) {
; #pragma unroll
;     for (int r = 0; r < 16; ++r) p[r] = __builtin_amdgcn_exp2f(p[r]);
;     float ps = 0.f;
; #pragma unroll
;     for (int r = 0; r < 16; ++r) ps += p[r];
;     l_reg += ps; asm volatile("" : "+v"(l_reg));
;     ...
;     ATT_PK4(p, 0, pa0); ATT_PK4(p, 8, pa1);
;     ...
; }
.LBB0_1924:
	s_add_i32 s3, s22, 0xffffc000
	s_and_b32 s3, s3, 0x6000
	v_add_u32_e32 v196, s3, v107
	v_add_u32_e32 v197, s3, v108
	v_add_u32_e32 v198, s3, v109
	v_add_u32_e32 v199, s3, v110
	ds_read_b128 v[124:127], v196
	ds_read_b128 v[132:135], v197
	ds_read_b128 v[136:139], v198
	ds_read_b128 v[140:143], v199
	ds_read_b64_tr_b16 v[144:145], v121 offset:0x2000
	ds_read_b64_tr_b16 v[146:147], v121 offset:0x2800
	ds_read_b64_tr_b16 v[148:149], v121 offset:0x3000
	ds_read_b64_tr_b16 v[150:151], v121 offset:0x3800
	ds_read_b64_tr_b16 v[152:153], v121 offset:0x2200
	ds_read_b64_tr_b16 v[154:155], v121 offset:0x2a00
	ds_read_b64_tr_b16 v[156:157], v121 offset:0x3200
	ds_read_b64_tr_b16 v[158:159], v121 offset:0x3a00
	ds_read_b64_tr_b16 v[162:163], v121 offset:0x2400
	ds_read_b64_tr_b16 v[164:165], v121 offset:0x2c00
	ds_read_b64_tr_b16 v[166:167], v121 offset:0x3400
	ds_read_b64_tr_b16 v[168:169], v121 offset:0x3c00
	ds_read_b64_tr_b16 v[170:171], v121 offset:0x2600
	ds_read_b64_tr_b16 v[172:173], v121 offset:0x2e00
	ds_read_b64_tr_b16 v[174:175], v121 offset:0x3600
	ds_read_b64_tr_b16 v[176:177], v121 offset:0x3e00
	s_setprio 2
	v_exp_f32_e32 v64, v64
	v_exp_f32_e32 v65, v65
	v_exp_f32_e32 v66, v66
	v_exp_f32_e32 v67, v67
	v_exp_f32_e32 v68, v68
	v_exp_f32_e32 v69, v69
	v_add_f32_e32 v121, v65, v64
	v_exp_f32_e32 v70, v70
	v_add_f32_e32 v121, v66, v121
	v_exp_f32_e32 v71, v71
	v_add_f32_e32 v121, v67, v121
	v_exp_f32_e32 v72, v72
	v_add_f32_e32 v121, v68, v121
	v_exp_f32_e32 v73, v73
	v_add_f32_e32 v121, v69, v121
	v_exp_f32_e32 v74, v74
	v_add_f32_e32 v121, v70, v121
	v_exp_f32_e32 v75, v75
	v_add_f32_e32 v121, v71, v121
	v_exp_f32_e32 v76, v76
	v_add_f32_e32 v121, v72, v121
	v_exp_f32_e32 v77, v77
	v_add_f32_e32 v121, v73, v121
	v_exp_f32_e32 v78, v78
	v_add_f32_e32 v121, v74, v121
	v_exp_f32_e32 v79, v79
	v_add_f32_e32 v121, v75, v121
	v_cvt_pk_bf16_f32 v64, v64, v65
	v_add_f32_e32 v121, v76, v121
	v_cvt_pk_bf16_f32 v65, v66, v67
	v_add_f32_e32 v121, v77, v121
	v_cvt_pk_bf16_f32 v66, v68, v69
	v_add_f32_e32 v121, v78, v121
	v_cvt_pk_bf16_f32 v67, v70, v71
	v_add_f32_e32 v121, v79, v121
	v_cvt_pk_bf16_f32 v68, v72, v73
	v_add_f32_e32 v120, v120, v121
	v_cvt_pk_bf16_f32 v69, v74, v75
	v_cvt_pk_bf16_f32 v70, v76, v77
	v_cvt_pk_bf16_f32 v71, v78, v79
	s_waitcnt lgkmcnt(0)
	s_setprio 1
	v_mfma_f32_32x32x16_bf16 v[0:15], v[64:67], v[144:147], v[0:15]
	s_sub_i32 s74, s0, s55
	s_cmp_lt_u32 s74, s100
	v_mfma_f32_32x32x16_bf16 v[48:63], v[64:67], v[152:155], v[48:63]
	v_mfma_f32_32x32x16_bf16 v[32:47], v[64:67], v[162:165], v[32:47]
	v_mfma_f32_32x32x16_bf16 v[16:31], v[64:67], v[170:173], v[16:31]
	v_mfma_f32_32x32x16_bf16 v[0:15], v[68:71], v[148:151], v[0:15]
	v_mfma_f32_32x32x16_bf16 v[48:63], v[68:71], v[156:159], v[48:63]
	v_mfma_f32_32x32x16_bf16 v[32:47], v[68:71], v[166:169], v[32:47]
	v_mfma_f32_32x32x16_bf16 v[16:31], v[68:71], v[174:177], v[16:31]
	v_mfma_f32_32x32x16_bf16 v[64:79], v[124:127], v[92:95], 0
	v_mfma_f32_32x32x16_bf16 v[64:79], v[132:135], v[88:91], v[64:79]
	v_mfma_f32_32x32x16_bf16 v[64:79], v[136:139], v[84:87], v[64:79]
	v_mfma_f32_32x32x16_bf16 v[64:79], v[140:143], v[80:83], v[64:79]
	s_cbranch_scc1 .Ldt_d0_bias2

; #define SBAR() __builtin_amdgcn_sched_barrier(0)
; #define ATT_DMA_K(t) do { const bf16_t* kg_ = Kh + (size_t)(t) * 64 * LDK; LAS unsigned char* sb_ = lds + ((t) & 3) * KBUF; \
;     _Pragma("unroll") for (int i_ = 0; i_ < NKP; ++i_) __builtin_amdgcn_global_load_lds((const unsigned*)(kg_ + kgo[i_]), (LAS unsigned*)(sb_ + (wid + 8 * i_) * 1024), 16, 0, 0); } while (0)
; #define ATT_DMA_V(t, vs) do { const bf16_t* vg_ = Vh + (size_t)(t) * 64 * LDV; LAS unsigned char* sb_ = lds + V_OFF + (vs) * SHM_V; \
;     _Pragma("unroll") for (int i_ = 0; i_ < 2; ++i_) __builtin_amdgcn_global_load_lds((const unsigned*)(vg_ + vgo[i_]), (LAS unsigned*)(sb_ + (2 * wid + i_) * 1024), 16, 0, 0); } while (0)
; #define ATT_SEG(t) do { if constexpr (MODE != 0) { if (((t) == tL && tL > 0) || (t) == tR) { const float f_ = (t) == tR ? fR : fL; l_reg *= f_; \
;     _Pragma("unroll") for (int d = 0; d < 4; ++d) _Pragma("unroll") for (int r = 0; r < 16; ++r) o[d][r] *= f_; } } } while (0)
; #define ATT_TOP(N) do { asm volatile("s_waitcnt vmcnt(%0)" :: "n"(N) : "memory"); __builtin_amdgcn_s_barrier(); asm volatile("" ::: "memory"); } while (0)
; DI void expsum(f32x16& p, float& l_reg, bf16x8& pa0, bf16x8& pa1) {
; #pragma unroll
;     for (int r = 0; r < 16; ++r) p[r] = __builtin_amdgcn_exp2f(p[r]);
;     float ps = 0.f;
; #pragma unroll
;     for (int r = 0; r < 16; ++r) ps += p[r];
;     l_reg += ps; asm volatile("" : "+v"(l_reg));
;     ...
;     ATT_PK4(p, 0, pa0); ATT_PK4(p, 8, pa1);
;     ...
; }
; template <int DQK, int MODE, int LDQ, int LDK, int LDV> ...
;     ...
;     f32x16 pA, pB; bf16x8 pa0, pa1;
;     int v0 = 0, v1 = 1, v2 = 2;
;     ATT_TOP(NKP + 2);
;     { bf16x8 kf[NDA]; k_reads<DQK, 0, NDA>(kf, lds, 0, r32, hi); ATT_LGKM0(); qk_mma<0, NDA>(pA, kf, qr);
;       if constexpr (ND0 > NDA) { bf16x8 kg[ND0 - NDA]; k_reads<DQK, NDA, ND0>(kg, lds, 0, r32, hi); ATT_LGKM0(); qk_mma<NDA, ND0>(pA, kg, qr); }
;       ATT_BIAS(pA, 0, 0); }
;     if (wid >= 4) __builtin_amdgcn_s_setprio(1);
;     for (int j = 0; j < NT; ++j) {
;         if (j + 2 < NT) ATT_TOP(NKP + 2); else ATT_TOP(0);
;         if (j + 3 < NT) ATT_DMA_K(j + 3);
;         if (j + 2 < NT) ATT_DMA_V(j + 2, v2);
;         ATT_SEG(j); SBAR();
;         ATT_STEP(pA, pB, 0, v0, true, 1, j);
;         ATT_STEP(pB, pA, 1, v0, (j + 1 < NT), 0, j + 1);
.Lhw_d1_b_n1953:
	ds_read_b128 v[122:125], v196 offset:4096
	ds_read_b128 v[132:135], v197 offset:4096
	s_lshl_b32 s2, s23, 14
	ds_read_b128 v[136:139], v198 offset:4096
	ds_read_b128 v[140:143], v199 offset:4096
	v_add_u32_e32 v121, s2, v106
	ds_read_b64_tr_b16 v[144:145], v121 offset:0
	ds_read_b64_tr_b16 v[146:147], v121 offset:0x800
	ds_read_b64_tr_b16 v[148:149], v121 offset:0x1000
	ds_read_b64_tr_b16 v[150:151], v121 offset:0x1800
	ds_read_b64_tr_b16 v[152:153], v121 offset:0x200
	ds_read_b64_tr_b16 v[154:155], v121 offset:0xa00
	ds_read_b64_tr_b16 v[156:157], v121 offset:0x1200
	ds_read_b64_tr_b16 v[158:159], v121 offset:0x1a00
	ds_read_b64_tr_b16 v[162:163], v121 offset:0x400
	ds_read_b64_tr_b16 v[164:165], v121 offset:0xc00
	ds_read_b64_tr_b16 v[166:167], v121 offset:0x1400
	ds_read_b64_tr_b16 v[168:169], v121 offset:0x1c00
	ds_read_b64_tr_b16 v[170:171], v121 offset:0x600
	ds_read_b64_tr_b16 v[172:173], v121 offset:0xe00
	ds_read_b64_tr_b16 v[174:175], v121 offset:0x1600
	ds_read_b64_tr_b16 v[176:177], v121 offset:0x1e00
	s_setprio 2
	v_exp_f32_e32 v64, v64
	v_exp_f32_e32 v65, v65
	v_exp_f32_e32 v66, v66
	v_exp_f32_e32 v67, v67
	v_exp_f32_e32 v68, v68
	v_exp_f32_e32 v69, v69
	v_add_f32_e32 v126, v65, v64
	v_exp_f32_e32 v70, v70
	v_add_f32_e32 v126, v66, v126
	v_exp_f32_e32 v71, v71
	v_add_f32_e32 v126, v67, v126
	v_exp_f32_e32 v72, v72
	v_add_f32_e32 v126, v68, v126
	v_exp_f32_e32 v73, v73
	v_add_f32_e32 v126, v69, v126
	v_exp_f32_e32 v74, v74
	v_add_f32_e32 v126, v70, v126
	v_exp_f32_e32 v75, v75
	v_add_f32_e32 v126, v71, v126
	v_exp_f32_e32 v76, v76
	v_add_f32_e32 v126, v72, v126
	v_exp_f32_e32 v77, v77
	v_add_f32_e32 v126, v73, v126
	v_exp_f32_e32 v78, v78
	v_add_f32_e32 v126, v74, v126
	v_exp_f32_e32 v79, v79
	v_add_f32_e32 v126, v75, v126
	v_cvt_pk_bf16_f32 v64, v64, v65
	v_add_f32_e32 v126, v76, v126
	v_cvt_pk_bf16_f32 v65, v66, v67
	v_add_f32_e32 v126, v77, v126
	v_cvt_pk_bf16_f32 v66, v68, v69
	v_add_f32_e32 v126, v78, v126
	v_cvt_pk_bf16_f32 v67, v70, v71
	v_add_f32_e32 v126, v79, v126
	v_cvt_pk_bf16_f32 v68, v72, v73
	v_add_f32_e32 v120, v126, v120
	v_cvt_pk_bf16_f32 v69, v74, v75
	v_cvt_pk_bf16_f32 v70, v76, v77
	v_cvt_pk_bf16_f32 v71, v78, v79
	s_waitcnt lgkmcnt(0)
	s_setprio 1
	v_mfma_f32_32x32x16_bf16 v[0:15], v[64:67], v[144:147], v[0:15]
	s_sub_i32 s3, s0, s98
	s_cmp_lt_u32 s3, s100
	v_mfma_f32_32x32x16_bf16 v[48:63], v[64:67], v[152:155], v[48:63]
	v_mfma_f32_32x32x16_bf16 v[16:31], v[64:67], v[162:165], v[16:31]
	v_mfma_f32_32x32x16_bf16 v[32:47], v[64:67], v[170:173], v[32:47]
	v_mfma_f32_32x32x16_bf16 v[0:15], v[68:71], v[148:151], v[0:15]
	v_mfma_f32_32x32x16_bf16 v[48:63], v[68:71], v[156:159], v[48:63]
	v_mfma_f32_32x32x16_bf16 v[16:31], v[68:71], v[166:169], v[16:31]
	v_mfma_f32_32x32x16_bf16 v[32:47], v[68:71], v[174:177], v[32:47]
	v_mfma_f32_32x32x16_bf16 v[64:79], v[122:125], v[92:95], 0
	v_mfma_f32_32x32x16_bf16 v[64:79], v[132:135], v[88:91], v[64:79]
	v_mfma_f32_32x32x16_bf16 v[64:79], v[136:139], v[84:87], v[64:79]
	v_mfma_f32_32x32x16_bf16 v[64:79], v[140:143], v[80:83], v[64:79]
	s_setprio 0
	s_cbranch_scc1 .Lhw_d1_b_dtd1bias1
.Lhw_d1_b_n1955:
	s_add_i32 s3, s22, 0xffffc000
	s_and_b32 s3, s3, 0x6000
	v_add_u32_e32 v196, s3, v107
	v_add_u32_e32 v197, s3, v108
	v_add_u32_e32 v198, s3, v109
	v_add_u32_e32 v199, s3, v110
	ds_read_b128 v[124:127], v196
	ds_read_b128 v[132:135], v197
	ds_read_b128 v[136:139], v198
	ds_read_b128 v[140:143], v199
	ds_read_b64_tr_b16 v[144:145], v121 offset:0x2000
	ds_read_b64_tr_b16 v[146:147], v121 offset:0x2800
	ds_read_b64_tr_b16 v[148:149], v121 offset:0x3000
	ds_read_b64_tr_b16 v[150:151], v121 offset:0x3800
	ds_read_b64_tr_b16 v[152:153], v121 offset:0x2200
	ds_read_b64_tr_b16 v[154:155], v121 offset:0x2a00
	ds_read_b64_tr_b16 v[156:157], v121 offset:0x3200
	ds_read_b64_tr_b16 v[158:159], v121 offset:0x3a00
	ds_read_b64_tr_b16 v[162:163], v121 offset:0x2400
	ds_read_b64_tr_b16 v[164:165], v121 offset:0x2c00
	ds_read_b64_tr_b16 v[166:167], v121 offset:0x3400
	ds_read_b64_tr_b16 v[168:169], v121 offset:0x3c00
	ds_read_b64_tr_b16 v[170:171], v121 offset:0x2600
	ds_read_b64_tr_b16 v[172:173], v121 offset:0x2e00
	ds_read_b64_tr_b16 v[174:175], v121 offset:0x3600
	ds_read_b64_tr_b16 v[176:177], v121 offset:0x3e00
	s_setprio 2
	v_exp_f32_e32 v64, v64
	v_exp_f32_e32 v65, v65
	v_exp_f32_e32 v66, v66
	v_exp_f32_e32 v67, v67
	v_exp_f32_e32 v68, v68
	v_exp_f32_e32 v69, v69
	v_add_f32_e32 v121, v65, v64
	v_exp_f32_e32 v70, v70
	v_add_f32_e32 v121, v66, v121
	v_exp_f32_e32 v71, v71
	v_add_f32_e32 v121, v67, v121
	v_exp_f32_e32 v72, v72
	v_add_f32_e32 v121, v68, v121
	v_exp_f32_e32 v73, v73
	v_add_f32_e32 v121, v69, v121
	v_exp_f32_e32 v74, v74
	v_add_f32_e32 v121, v70, v121
	v_exp_f32_e32 v75, v75
	v_add_f32_e32 v121, v71, v121
	v_exp_f32_e32 v76, v76
	v_add_f32_e32 v121, v72, v121
	v_exp_f32_e32 v77, v77
	v_add_f32_e32 v121, v73, v121
	v_exp_f32_e32 v78, v78
	v_add_f32_e32 v121, v74, v121
	v_exp_f32_e32 v79, v79
	v_add_f32_e32 v121, v75, v121
	v_cvt_pk_bf16_f32 v64, v64, v65
	v_add_f32_e32 v121, v76, v121
	v_cvt_pk_bf16_f32 v65, v66, v67
	v_add_f32_e32 v121, v77, v121
	v_cvt_pk_bf16_f32 v66, v68, v69
	v_add_f32_e32 v121, v78, v121
	v_cvt_pk_bf16_f32 v67, v70, v71
	v_add_f32_e32 v121, v79, v121
	v_cvt_pk_bf16_f32 v68, v72, v73
	v_add_f32_e32 v120, v120, v121
	v_cvt_pk_bf16_f32 v69, v74, v75
	v_cvt_pk_bf16_f32 v70, v76, v77
	v_cvt_pk_bf16_f32 v71, v78, v79
	s_waitcnt lgkmcnt(0)
	s_setprio 1
	s_waitcnt vmcnt(3)
	s_barrier
	v_mfma_f32_32x32x16_bf16 v[0:15], v[64:67], v[144:147], v[0:15]
	s_sub_i32 s74, s0, s47
	s_cmp_lt_u32 s74, s100
	v_mfma_f32_32x32x16_bf16 v[48:63], v[64:67], v[152:155], v[48:63]
	v_mfma_f32_32x32x16_bf16 v[16:31], v[64:67], v[162:165], v[16:31]
	v_mfma_f32_32x32x16_bf16 v[32:47], v[64:67], v[170:173], v[32:47]
	v_mfma_f32_32x32x16_bf16 v[0:15], v[68:71], v[148:151], v[0:15]
	v_mfma_f32_32x32x16_bf16 v[48:63], v[68:71], v[156:159], v[48:63]
	v_mfma_f32_32x32x16_bf16 v[16:31], v[68:71], v[166:169], v[16:31]
	v_mfma_f32_32x32x16_bf16 v[32:47], v[68:71], v[174:177], v[32:47]
	v_mfma_f32_32x32x16_bf16 v[64:79], v[124:127], v[92:95], 0
	v_mfma_f32_32x32x16_bf16 v[64:79], v[132:135], v[88:91], v[64:79]
	v_mfma_f32_32x32x16_bf16 v[64:79], v[136:139], v[84:87], v[64:79]
	v_mfma_f32_32x32x16_bf16 v[64:79], v[140:143], v[80:83], v[64:79]
	s_cbranch_scc1 .Lhw_d1_b_dtd1bias2

; DI void expsum(f32x16& p, float& l_reg, bf16x8& pa0, bf16x8& pa1) {
; #pragma unroll
;     for (int r = 0; r < 16; ++r) p[r] = __builtin_amdgcn_exp2f(p[r]);
;     float ps = 0.f;
; #pragma unroll
;     for (int r = 0; r < 16; ++r) ps += p[r];
;     l_reg += ps; asm volatile("" : "+v"(l_reg));
;     ...
;     ATT_PK4(p, 0, pa0); ATT_PK4(p, 8, pa1);
;     ...
; }
.LBB0_1955:
	s_add_i32 s3, s22, 0xffffc000
	s_and_b32 s3, s3, 0x6000
	v_add_u32_e32 v196, s3, v107
	v_add_u32_e32 v197, s3, v108
	v_add_u32_e32 v198, s3, v109
	v_add_u32_e32 v199, s3, v110
	ds_read_b128 v[124:127], v196
	ds_read_b128 v[132:135], v197
	ds_read_b128 v[136:139], v198
	ds_read_b128 v[140:143], v199
	ds_read_b64_tr_b16 v[144:145], v121 offset:0x2000
	ds_read_b64_tr_b16 v[146:147], v121 offset:0x2800
	ds_read_b64_tr_b16 v[148:149], v121 offset:0x3000
	ds_read_b64_tr_b16 v[150:151], v121 offset:0x3800
	ds_read_b64_tr_b16 v[152:153], v121 offset:0x2200
	ds_read_b64_tr_b16 v[154:155], v121 offset:0x2a00
	ds_read_b64_tr_b16 v[156:157], v121 offset:0x3200
	ds_read_b64_tr_b16 v[158:159], v121 offset:0x3a00
	ds_read_b64_tr_b16 v[162:163], v121 offset:0x2400
	ds_read_b64_tr_b16 v[164:165], v121 offset:0x2c00
	ds_read_b64_tr_b16 v[166:167], v121 offset:0x3400
	ds_read_b64_tr_b16 v[168:169], v121 offset:0x3c00
	ds_read_b64_tr_b16 v[170:171], v121 offset:0x2600
	ds_read_b64_tr_b16 v[172:173], v121 offset:0x2e00
	ds_read_b64_tr_b16 v[174:175], v121 offset:0x3600
	ds_read_b64_tr_b16 v[176:177], v121 offset:0x3e00
	s_setprio 2
	v_exp_f32_e32 v64, v64
	v_exp_f32_e32 v65, v65
	v_exp_f32_e32 v66, v66
	v_exp_f32_e32 v67, v67
	v_exp_f32_e32 v68, v68
	v_exp_f32_e32 v69, v69
	v_add_f32_e32 v121, v65, v64
	v_exp_f32_e32 v70, v70
	v_add_f32_e32 v121, v66, v121
	v_exp_f32_e32 v71, v71
	v_add_f32_e32 v121, v67, v121
	v_exp_f32_e32 v72, v72
	v_add_f32_e32 v121, v68, v121
	v_exp_f32_e32 v73, v73
	v_add_f32_e32 v121, v69, v121
	v_exp_f32_e32 v74, v74
	v_add_f32_e32 v121, v70, v121
	v_exp_f32_e32 v75, v75
	v_add_f32_e32 v121, v71, v121
	v_exp_f32_e32 v76, v76
	v_add_f32_e32 v121, v72, v121
	v_exp_f32_e32 v77, v77
	v_add_f32_e32 v121, v73, v121
	v_exp_f32_e32 v78, v78
	v_add_f32_e32 v121, v74, v121
	v_exp_f32_e32 v79, v79
	v_add_f32_e32 v121, v75, v121
	v_cvt_pk_bf16_f32 v64, v64, v65
	v_add_f32_e32 v121, v76, v121
	v_cvt_pk_bf16_f32 v65, v66, v67
	v_add_f32_e32 v121, v77, v121
	v_cvt_pk_bf16_f32 v66, v68, v69
	v_add_f32_e32 v121, v78, v121
	v_cvt_pk_bf16_f32 v67, v70, v71
	v_add_f32_e32 v121, v79, v121
	v_cvt_pk_bf16_f32 v68, v72, v73
	v_add_f32_e32 v120, v120, v121
	v_cvt_pk_bf16_f32 v69, v74, v75
	v_cvt_pk_bf16_f32 v70, v76, v77
	v_cvt_pk_bf16_f32 v71, v78, v79
	s_waitcnt lgkmcnt(0)
	s_setprio 1
	v_mfma_f32_32x32x16_bf16 v[0:15], v[64:67], v[144:147], v[0:15]
	s_sub_i32 s74, s0, s47
	s_cmp_lt_u32 s74, s100
	v_mfma_f32_32x32x16_bf16 v[48:63], v[64:67], v[152:155], v[48:63]
	v_mfma_f32_32x32x16_bf16 v[16:31], v[64:67], v[162:165], v[16:31]
	v_mfma_f32_32x32x16_bf16 v[32:47], v[64:67], v[170:173], v[32:47]
	v_mfma_f32_32x32x16_bf16 v[0:15], v[68:71], v[148:151], v[0:15]
	v_mfma_f32_32x32x16_bf16 v[48:63], v[68:71], v[156:159], v[48:63]
	v_mfma_f32_32x32x16_bf16 v[16:31], v[68:71], v[166:169], v[16:31]
	v_mfma_f32_32x32x16_bf16 v[32:47], v[68:71], v[174:177], v[32:47]
	v_mfma_f32_32x32x16_bf16 v[64:79], v[124:127], v[92:95], 0
	v_mfma_f32_32x32x16_bf16 v[64:79], v[132:135], v[88:91], v[64:79]
	v_mfma_f32_32x32x16_bf16 v[64:79], v[136:139], v[84:87], v[64:79]
	v_mfma_f32_32x32x16_bf16 v[64:79], v[140:143], v[80:83], v[64:79]
	s_cbranch_scc1 .Ldt_d1_bias2

; #define SBAR() __builtin_amdgcn_sched_barrier(0)
; #define ATT_DMA_K(t) do { const bf16_t* kg_ = Kh + (size_t)(t) * 64 * LDK; LAS unsigned char* sb_ = lds + ((t) & 3) * KBUF; \
;     _Pragma("unroll") for (int i_ = 0; i_ < NKP; ++i_) __builtin_amdgcn_global_load_lds((const unsigned*)(kg_ + kgo[i_]), (LAS unsigned*)(sb_ + (wid + 8 * i_) * 1024), 16, 0, 0); } while (0)
; #define ATT_DMA_V(t, vs) do { const bf16_t* vg_ = Vh + (size_t)(t) * 64 * LDV; LAS unsigned char* sb_ = lds + V_OFF + (vs) * SHM_V; \
;     _Pragma("unroll") for (int i_ = 0; i_ < 2; ++i_) __builtin_amdgcn_global_load_lds((const unsigned*)(vg_ + vgo[i_]), (LAS unsigned*)(sb_ + (2 * wid + i_) * 1024), 16, 0, 0); } while (0)
; #define ATT_SEG(t) do { if constexpr (MODE != 0) { if (((t) == tL && tL > 0) || (t) == tR) { const float f_ = (t) == tR ? fR : fL; l_reg *= f_; \
;     _Pragma("unroll") for (int d = 0; d < 4; ++d) _Pragma("unroll") for (int r = 0; r < 16; ++r) o[d][r] *= f_; } } } while (0)
; #define ATT_TOP(N) do { asm volatile("s_waitcnt vmcnt(%0)" :: "n"(N) : "memory"); __builtin_amdgcn_s_barrier(); asm volatile("" ::: "memory"); } while (0)
; DI void expsum(f32x16& p, float& l_reg, bf16x8& pa0, bf16x8& pa1) {
; #pragma unroll
;     for (int r = 0; r < 16; ++r) p[r] = __builtin_amdgcn_exp2f(p[r]);
;     float ps = 0.f;
; #pragma unroll
;     for (int r = 0; r < 16; ++r) ps += p[r];
;     l_reg += ps; asm volatile("" : "+v"(l_reg));
;     ...
;     ATT_PK4(p, 0, pa0); ATT_PK4(p, 8, pa1);
;     ...
; }
; template <int DQK, int MODE, int LDQ, int LDK, int LDV> ...
;     ...
;     f32x16 pA, pB; bf16x8 pa0, pa1;
;     int v0 = 0, v1 = 1, v2 = 2;
;     ATT_TOP(NKP + 2);
;     { bf16x8 kf[NDA]; k_reads<DQK, 0, NDA>(kf, lds, 0, r32, hi); ATT_LGKM0(); qk_mma<0, NDA>(pA, kf, qr);
;       if constexpr (ND0 > NDA) { bf16x8 kg[ND0 - NDA]; k_reads<DQK, NDA, ND0>(kg, lds, 0, r32, hi); ATT_LGKM0(); qk_mma<NDA, ND0>(pA, kg, qr); }
;       ATT_BIAS(pA, 0, 0); }
;     if (wid >= 4) __builtin_amdgcn_s_setprio(1);
;     for (int j = 0; j < NT; ++j) {
;         if (j + 2 < NT) ATT_TOP(NKP + 2); else ATT_TOP(0);
;         if (j + 3 < NT) ATT_DMA_K(j + 3);
;         if (j + 2 < NT) ATT_DMA_V(j + 2, v2);
;         ATT_SEG(j); SBAR();
;         ATT_STEP(pA, pB, 0, v0, true, 1, j);
;         ATT_STEP(pB, pA, 1, v0, (j + 1 < NT), 0, j + 1);
.Lhw_mla_b_n1982:
	s_and_b32 s1, s43, 3
	s_mulk_i32 s1, 0x6000
	s_add_i32 s1, s49, s1
	s_setprio 0
	s_mov_b32 m0, s1
	s_mov_b32 s0, s5
	s_mov_b32 s5, s44
	s_mov_b32 s44, s4
	s_lshl_b32 s4, s4, 14
	global_load_lds_dwordx4 v136, s[34:35]
	s_add_i32 m0, s1, 0x2000
	s_add_i32 s4, s52, s4
	global_load_lds_dwordx4 v138, s[34:35]
	s_add_i32 m0, s1, 0x4000
	s_add_i32 s6, s4, 0x400
	global_load_lds_dwordx4 v140, s[34:35]
	s_mov_b32 m0, s4
	s_add_i32 s1, s43, -3
	global_load_lds_dwordx4 v144, s[34:35]
	s_mov_b32 m0, s6
	s_nop 0
	global_load_lds_dwordx4 v142, s[34:35]
	s_and_b32 s1, s1, 3
	s_mulk_i32 s1, 0x6000
	v_add_u32_e32 v246, s1, v158
	v_add_u32_e32 v250, v246, v151
	v_add_u32_e32 v251, v246, v149
	v_add_u32_e32 v252, v246, v148
	v_add_u32_e32 v253, v246, v147
	s_lshl_b32 s1, s0, 14
	ds_read_b128 v[190:193], v250 offset:12416
	ds_read_b128 v[194:197], v251 offset:12416
	ds_read_b128 v[174:177], v250 offset:12288
	ds_read_b128 v[178:181], v251 offset:12288
	ds_read_b128 v[182:185], v252 offset:12288
	ds_read_b128 v[186:189], v253 offset:12288
	v_add_u32_e32 v254, s1, v130
	ds_read_b64_tr_b16 v[198:199], v254 offset:0
	ds_read_b64_tr_b16 v[200:201], v254 offset:0x800
	ds_read_b64_tr_b16 v[202:203], v254 offset:0x1000
	ds_read_b64_tr_b16 v[204:205], v254 offset:0x1800
	ds_read_b64_tr_b16 v[206:207], v254 offset:0x200
	ds_read_b64_tr_b16 v[208:209], v254 offset:0xa00
	ds_read_b64_tr_b16 v[210:211], v254 offset:0x1200
	ds_read_b64_tr_b16 v[212:213], v254 offset:0x1a00
	ds_read_b64_tr_b16 v[214:215], v254 offset:0x400
	ds_read_b64_tr_b16 v[216:217], v254 offset:0xc00
	ds_read_b64_tr_b16 v[218:219], v254 offset:0x1400
	ds_read_b64_tr_b16 v[220:221], v254 offset:0x1c00
	ds_read_b64_tr_b16 v[222:223], v254 offset:0x600
	ds_read_b64_tr_b16 v[224:225], v254 offset:0xe00
	ds_read_b64_tr_b16 v[226:227], v254 offset:0x1600
	ds_read_b64_tr_b16 v[228:229], v254 offset:0x1e00
	s_setprio 2
	v_exp_f32_e32 v64, v64
	v_exp_f32_e32 v65, v65
	v_exp_f32_e32 v66, v66
	v_exp_f32_e32 v67, v67
	v_exp_f32_e32 v68, v68
	v_exp_f32_e32 v69, v69
	v_add_f32_e32 v230, v65, v64
	v_exp_f32_e32 v70, v70
	v_add_f32_e32 v230, v66, v230
	v_exp_f32_e32 v71, v71
	v_add_f32_e32 v230, v67, v230
	v_exp_f32_e32 v72, v72
	v_add_f32_e32 v230, v68, v230
	v_exp_f32_e32 v73, v73
	v_add_f32_e32 v230, v69, v230
	v_exp_f32_e32 v74, v74
	v_add_f32_e32 v230, v70, v230
	v_exp_f32_e32 v75, v75
	v_add_f32_e32 v230, v71, v230
	v_exp_f32_e32 v76, v76
	v_add_f32_e32 v230, v72, v230
	v_exp_f32_e32 v77, v77
	v_add_f32_e32 v230, v73, v230
	v_exp_f32_e32 v78, v78
	v_add_f32_e32 v230, v74, v230
	v_exp_f32_e32 v79, v79
	v_add_f32_e32 v230, v75, v230
	v_cvt_pk_bf16_f32 v64, v64, v65
	v_add_f32_e32 v230, v76, v230
	v_cvt_pk_bf16_f32 v65, v66, v67
	v_add_f32_e32 v230, v77, v230
	v_cvt_pk_bf16_f32 v66, v68, v69
	v_add_f32_e32 v230, v78, v230
	v_cvt_pk_bf16_f32 v67, v70, v71
	v_add_f32_e32 v230, v79, v230
	v_cvt_pk_bf16_f32 v68, v72, v73
	v_add_f32_e32 v173, v173, v230
	v_cvt_pk_bf16_f32 v69, v74, v75
	v_cvt_pk_bf16_f32 v70, v76, v77
	v_cvt_pk_bf16_f32 v71, v78, v79
	s_waitcnt lgkmcnt(0)
	ds_read_b128 v[230:233], v252 offset:12416
	ds_read_b128 v[234:237], v253 offset:12416
	ds_read_b128 v[238:241], v250 offset:12544
	ds_read_b128 v[242:245], v251 offset:12544
	ds_read_b128 v[246:249], v252 offset:12544
	ds_read_b128 v[250:253], v253 offset:12544
	s_setprio 1
	v_mfma_f32_32x32x16_bf16 v[48:63], v[64:67], v[198:201], v[48:63]
	v_mfma_f32_32x32x16_bf16 v[32:47], v[64:67], v[206:209], v[32:47]
	v_mfma_f32_32x32x16_bf16 v[16:31], v[64:67], v[214:217], v[16:31]
	v_mfma_f32_32x32x16_bf16 v[0:15], v[64:67], v[222:225], v[0:15]
	v_mfma_f32_32x32x16_bf16 v[48:63], v[68:71], v[202:205], v[48:63]
	v_mfma_f32_32x32x16_bf16 v[32:47], v[68:71], v[210:213], v[32:47]
	v_mfma_f32_32x32x16_bf16 v[16:31], v[68:71], v[218:221], v[16:31]
	v_mfma_f32_32x32x16_bf16 v[0:15], v[68:71], v[226:229], v[0:15]
	s_waitcnt lgkmcnt(0)
	v_mfma_f32_32x32x16_bf16 v[64:79], v[174:177], v[80:83], 0
	v_mfma_f32_32x32x16_bf16 v[64:79], v[178:181], v[84:87], v[64:79]
	v_mfma_f32_32x32x16_bf16 v[64:79], v[182:185], v[88:91], v[64:79]
	v_mfma_f32_32x32x16_bf16 v[64:79], v[186:189], v[92:95], v[64:79]
	v_mfma_f32_32x32x16_bf16 v[64:79], v[190:193], v[96:99], v[64:79]
	v_mfma_f32_32x32x16_bf16 v[64:79], v[194:197], v[100:103], v[64:79]
	v_mfma_f32_32x32x16_bf16 v[64:79], v[230:233], v[104:107], v[64:79]
	v_mfma_f32_32x32x16_bf16 v[64:79], v[234:237], v[108:111], v[64:79]
	v_mfma_f32_32x32x16_bf16 v[64:79], v[238:241], v[112:115], v[64:79]
	v_mfma_f32_32x32x16_bf16 v[64:79], v[242:245], v[116:119], v[64:79]
	v_mfma_f32_32x32x16_bf16 v[64:79], v[246:249], v[120:123], v[64:79]
	v_mfma_f32_32x32x16_bf16 v[64:79], v[250:253], v[124:127], v[64:79]
	s_setprio 0
	s_add_i32 s4, s43, -2
	s_and_b32 s4, s4, 3
	s_mulk_i32 s4, 0x6000
	v_add_u32_e32 v246, s4, v158
	v_add_u32_e32 v250, v246, v151
	v_add_u32_e32 v251, v246, v149
	v_add_u32_e32 v252, v246, v148
	v_add_u32_e32 v253, v246, v147
	ds_read_b128 v[190:193], v250 offset:128
	ds_read_b128 v[194:197], v251 offset:128
	ds_read_b128 v[174:177], v250
	ds_read_b128 v[178:181], v251
	ds_read_b128 v[182:185], v252
	ds_read_b128 v[186:189], v253
	ds_read_b64_tr_b16 v[198:199], v254 offset:0x2000
	ds_read_b64_tr_b16 v[200:201], v254 offset:0x2800
	ds_read_b64_tr_b16 v[202:203], v254 offset:0x3000
	ds_read_b64_tr_b16 v[204:205], v254 offset:0x3800
	ds_read_b64_tr_b16 v[206:207], v254 offset:0x2200
	ds_read_b64_tr_b16 v[208:209], v254 offset:0x2a00
	ds_read_b64_tr_b16 v[210:211], v254 offset:0x3200
	ds_read_b64_tr_b16 v[212:213], v254 offset:0x3a00
	ds_read_b64_tr_b16 v[214:215], v254 offset:0x2400
	ds_read_b64_tr_b16 v[216:217], v254 offset:0x2c00
; #define SBAR() __builtin_amdgcn_sched_barrier(0)
; #define ATT_DMA_K(t) do { const bf16_t* kg_ = Kh + (size_t)(t) * 64 * LDK; LAS unsigned char* sb_ = lds + ((t) & 3) * KBUF; \
;     _Pragma("unroll") for (int i_ = 0; i_ < NKP; ++i_) __builtin_amdgcn_global_load_lds((const unsigned*)(kg_ + kgo[i_]), (LAS unsigned*)(sb_ + (wid + 8 * i_) * 1024), 16, 0, 0); } while (0)
; #define ATT_DMA_V(t, vs) do { const bf16_t* vg_ = Vh + (size_t)(t) * 64 * LDV; LAS unsigned char* sb_ = lds + V_OFF + (vs) * SHM_V; \
;     _Pragma("unroll") for (int i_ = 0; i_ < 2; ++i_) __builtin_amdgcn_global_load_lds((const unsigned*)(vg_ + vgo[i_]), (LAS unsigned*)(sb_ + (2 * wid + i_) * 1024), 16, 0, 0); } while (0)
; #define ATT_SEG(t) do { if constexpr (MODE != 0) { if (((t) == tL && tL > 0) || (t) == tR) { const float f_ = (t) == tR ? fR : fL; l_reg *= f_; \
;     _Pragma("unroll") for (int d = 0; d < 4; ++d) _Pragma("unroll") for (int r = 0; r < 16; ++r) o[d][r] *= f_; } } } while (0)
; #define ATT_TOP(N) do { asm volatile("s_waitcnt vmcnt(%0)" :: "n"(N) : "memory"); __builtin_amdgcn_s_barrier(); asm volatile("" ::: "memory"); } while (0)
; DI void expsum(f32x16& p, float& l_reg, bf16x8& pa0, bf16x8& pa1) {
; #pragma unroll
;     for (int r = 0; r < 16; ++r) p[r] = __builtin_amdgcn_exp2f(p[r]);
;     float ps = 0.f;
; #pragma unroll
;     for (int r = 0; r < 16; ++r) ps += p[r];
;     l_reg += ps; asm volatile("" : "+v"(l_reg));
;     ...
;     ATT_PK4(p, 0, pa0); ATT_PK4(p, 8, pa1);
;     ...
; }
; template <int DQK, int MODE, int LDQ, int LDK, int LDV> ...
;     ...
;     f32x16 pA, pB; bf16x8 pa0, pa1;
;     int v0 = 0, v1 = 1, v2 = 2;
;     ATT_TOP(NKP + 2);
;     { bf16x8 kf[NDA]; k_reads<DQK, 0, NDA>(kf, lds, 0, r32, hi); ATT_LGKM0(); qk_mma<0, NDA>(pA, kf, qr);
;       if constexpr (ND0 > NDA) { bf16x8 kg[ND0 - NDA]; k_reads<DQK, NDA, ND0>(kg, lds, 0, r32, hi); ATT_LGKM0(); qk_mma<NDA, ND0>(pA, kg, qr); }
;       ATT_BIAS(pA, 0, 0); }
;     if (wid >= 4) __builtin_amdgcn_s_setprio(1);
;     for (int j = 0; j < NT; ++j) {
;         if (j + 2 < NT) ATT_TOP(NKP + 2); else ATT_TOP(0);
;         if (j + 3 < NT) ATT_DMA_K(j + 3);
;         if (j + 2 < NT) ATT_DMA_V(j + 2, v2);
;         ATT_SEG(j); SBAR();
;         ATT_STEP(pA, pB, 0, v0, true, 1, j);
;         ATT_STEP(pB, pA, 1, v0, (j + 1 < NT), 0, j + 1);
;         { const int t_ = v0; v0 = v1; v1 = v2; v2 = t_; }
;     }
	ds_read_b64_tr_b16 v[218:219], v254 offset:0x3400
	ds_read_b64_tr_b16 v[220:221], v254 offset:0x3c00
	ds_read_b64_tr_b16 v[222:223], v254 offset:0x2600
	ds_read_b64_tr_b16 v[224:225], v254 offset:0x2e00
	ds_read_b64_tr_b16 v[226:227], v254 offset:0x3600
	ds_read_b64_tr_b16 v[228:229], v254 offset:0x3e00
	s_setprio 2
	v_exp_f32_e32 v64, v64
	v_exp_f32_e32 v65, v65
	v_exp_f32_e32 v66, v66
	v_exp_f32_e32 v67, v67
	v_exp_f32_e32 v68, v68
	v_exp_f32_e32 v69, v69
	v_add_f32_e32 v230, v65, v64
	v_exp_f32_e32 v70, v70
	v_add_f32_e32 v230, v66, v230
	v_exp_f32_e32 v71, v71
	v_add_f32_e32 v230, v67, v230
	v_exp_f32_e32 v72, v72
	v_add_f32_e32 v230, v68, v230
	v_exp_f32_e32 v73, v73
	v_add_f32_e32 v230, v69, v230
	v_exp_f32_e32 v74, v74
	v_add_f32_e32 v230, v70, v230
	v_exp_f32_e32 v75, v75
	v_add_f32_e32 v230, v71, v230
	v_exp_f32_e32 v76, v76
	v_add_f32_e32 v230, v72, v230
	v_exp_f32_e32 v77, v77
	v_add_f32_e32 v230, v73, v230
	v_exp_f32_e32 v78, v78
	v_add_f32_e32 v230, v74, v230
	v_exp_f32_e32 v79, v79
	v_add_f32_e32 v230, v75, v230
	v_cvt_pk_bf16_f32 v64, v64, v65
	v_add_f32_e32 v230, v76, v230
	v_cvt_pk_bf16_f32 v65, v66, v67
	v_add_f32_e32 v230, v77, v230
	v_cvt_pk_bf16_f32 v66, v68, v69
	v_add_f32_e32 v230, v78, v230
	v_cvt_pk_bf16_f32 v67, v70, v71
	v_add_f32_e32 v230, v79, v230
	v_cvt_pk_bf16_f32 v68, v72, v73
	v_add_f32_e32 v173, v173, v230
	v_cvt_pk_bf16_f32 v69, v74, v75
	v_cvt_pk_bf16_f32 v70, v76, v77
	v_cvt_pk_bf16_f32 v71, v78, v79
	s_waitcnt lgkmcnt(0)
	ds_read_b128 v[230:233], v252 offset:128
	ds_read_b128 v[234:237], v253 offset:128
	ds_read_b128 v[238:241], v250 offset:256
	ds_read_b128 v[242:245], v251 offset:256
	ds_read_b128 v[246:249], v252 offset:256
	ds_read_b128 v[250:253], v253 offset:256
	s_setprio 1
	s_waitcnt vmcnt(5)
	s_barrier
	v_mfma_f32_32x32x16_bf16 v[48:63], v[64:67], v[198:201], v[48:63]
	v_mfma_f32_32x32x16_bf16 v[32:47], v[64:67], v[206:209], v[32:47]
	v_mfma_f32_32x32x16_bf16 v[16:31], v[64:67], v[214:217], v[16:31]
	v_mfma_f32_32x32x16_bf16 v[0:15], v[64:67], v[222:225], v[0:15]
	v_mfma_f32_32x32x16_bf16 v[48:63], v[68:71], v[202:205], v[48:63]
	v_mfma_f32_32x32x16_bf16 v[32:47], v[68:71], v[210:213], v[32:47]
	v_mfma_f32_32x32x16_bf16 v[16:31], v[68:71], v[218:221], v[16:31]
	v_mfma_f32_32x32x16_bf16 v[0:15], v[68:71], v[226:229], v[0:15]
	s_waitcnt lgkmcnt(0)
	v_mfma_f32_32x32x16_bf16 v[64:79], v[174:177], v[80:83], 0
	v_mfma_f32_32x32x16_bf16 v[64:79], v[178:181], v[84:87], v[64:79]
	v_mfma_f32_32x32x16_bf16 v[64:79], v[182:185], v[88:91], v[64:79]
	v_mfma_f32_32x32x16_bf16 v[64:79], v[186:189], v[92:95], v[64:79]
	v_mfma_f32_32x32x16_bf16 v[64:79], v[190:193], v[96:99], v[64:79]
	v_mfma_f32_32x32x16_bf16 v[64:79], v[194:197], v[100:103], v[64:79]
	v_mfma_f32_32x32x16_bf16 v[64:79], v[230:233], v[104:107], v[64:79]
	v_mfma_f32_32x32x16_bf16 v[64:79], v[234:237], v[108:111], v[64:79]
	v_mfma_f32_32x32x16_bf16 v[64:79], v[238:241], v[112:115], v[64:79]
	v_mfma_f32_32x32x16_bf16 v[64:79], v[242:245], v[116:119], v[64:79]
	v_mfma_f32_32x32x16_bf16 v[64:79], v[246:249], v[120:123], v[64:79]
	v_mfma_f32_32x32x16_bf16 v[64:79], v[250:253], v[124:127], v[64:79]
	s_add_i32 s43, s43, 1
	v_add_u32_e32 v136, s36, v136
	v_add_u32_e32 v138, s36, v138
	v_add_u32_e32 v140, s36, v140
	v_add_u32_e32 v142, s38, v142
	v_add_u32_e32 v144, s38, v144
	s_cmp_eq_u32 s43, 64
	s_mov_b32 s4, s0
	s_cbranch_scc0 .Lhw_mla_b_n1982
	s_branch .Lhw_mla_exit
.LBB0_1982:
	s_and_b32 s1, s43, 3
	s_mulk_i32 s1, 0x6000
	s_add_i32 s1, s49, s1
	s_waitcnt vmcnt(5)
	s_barrier
	s_setprio 0
	s_mov_b32 m0, s1
	s_mov_b32 s0, s5
	s_mov_b32 s5, s44
	s_mov_b32 s44, s4
	s_lshl_b32 s4, s4, 14
	global_load_lds_dwordx4 v136, s[34:35]
	s_add_i32 m0, s1, 0x2000
	s_add_i32 s4, s52, s4
	global_load_lds_dwordx4 v138, s[34:35]
	s_add_i32 m0, s1, 0x4000
	s_add_i32 s6, s4, 0x400
	global_load_lds_dwordx4 v140, s[34:35]
	s_mov_b32 m0, s4
	s_add_i32 s1, s43, -3
	global_load_lds_dwordx4 v144, s[34:35]
	s_mov_b32 m0, s6
	s_nop 0
	global_load_lds_dwordx4 v142, s[34:35]
	s_and_b32 s1, s1, 3
	s_mulk_i32 s1, 0x6000
	v_add_u32_e32 v246, s1, v158
	v_add_u32_e32 v250, v246, v151
	v_add_u32_e32 v251, v246, v149
	v_add_u32_e32 v252, v246, v148
	v_add_u32_e32 v253, v246, v147
	s_lshl_b32 s1, s0, 14
	ds_read_b128 v[190:193], v250 offset:12416
	ds_read_b128 v[194:197], v251 offset:12416
	ds_read_b128 v[174:177], v250 offset:12288
	ds_read_b128 v[178:181], v251 offset:12288
	ds_read_b128 v[182:185], v252 offset:12288
	ds_read_b128 v[186:189], v253 offset:12288
	v_add_u32_e32 v254, s1, v130
	ds_read_b64_tr_b16 v[198:199], v254 offset:0
	ds_read_b64_tr_b16 v[200:201], v254 offset:0x800
	ds_read_b64_tr_b16 v[202:203], v254 offset:0x1000
	ds_read_b64_tr_b16 v[204:205], v254 offset:0x1800
	ds_read_b64_tr_b16 v[206:207], v254 offset:0x200
	ds_read_b64_tr_b16 v[208:209], v254 offset:0xa00
	ds_read_b64_tr_b16 v[210:211], v254 offset:0x1200
	ds_read_b64_tr_b16 v[212:213], v254 offset:0x1a00
	ds_read_b64_tr_b16 v[214:215], v254 offset:0x400
	ds_read_b64_tr_b16 v[216:217], v254 offset:0xc00
	ds_read_b64_tr_b16 v[218:219], v254 offset:0x1400
	ds_read_b64_tr_b16 v[220:221], v254 offset:0x1c00
	ds_read_b64_tr_b16 v[222:223], v254 offset:0x600
	ds_read_b64_tr_b16 v[224:225], v254 offset:0xe00
	ds_read_b64_tr_b16 v[226:227], v254 offset:0x1600
	ds_read_b64_tr_b16 v[228:229], v254 offset:0x1e00
	s_setprio 2
	v_exp_f32_e32 v64, v64
	v_exp_f32_e32 v65, v65
	v_exp_f32_e32 v66, v66
	v_exp_f32_e32 v67, v67
	v_exp_f32_e32 v68, v68
	v_exp_f32_e32 v69, v69
	v_add_f32_e32 v230, v65, v64
	v_exp_f32_e32 v70, v70
	v_add_f32_e32 v230, v66, v230
	v_exp_f32_e32 v71, v71
	v_add_f32_e32 v230, v67, v230
	v_exp_f32_e32 v72, v72
	v_add_f32_e32 v230, v68, v230
	v_exp_f32_e32 v73, v73
	v_add_f32_e32 v230, v69, v230
	v_exp_f32_e32 v74, v74
	v_add_f32_e32 v230, v70, v230
	v_exp_f32_e32 v75, v75
	v_add_f32_e32 v230, v71, v230
	v_exp_f32_e32 v76, v76
	v_add_f32_e32 v230, v72, v230
	v_exp_f32_e32 v77, v77
	v_add_f32_e32 v230, v73, v230
	v_exp_f32_e32 v78, v78
	v_add_f32_e32 v230, v74, v230
	v_exp_f32_e32 v79, v79
	v_add_f32_e32 v230, v75, v230
	v_cvt_pk_bf16_f32 v64, v64, v65
	v_add_f32_e32 v230, v76, v230
	v_cvt_pk_bf16_f32 v65, v66, v67
	v_add_f32_e32 v230, v77, v230
	v_cvt_pk_bf16_f32 v66, v68, v69
	v_add_f32_e32 v230, v78, v230
	v_cvt_pk_bf16_f32 v67, v70, v71
	v_add_f32_e32 v230, v79, v230
	v_cvt_pk_bf16_f32 v68, v72, v73
	v_add_f32_e32 v173, v173, v230
	v_cvt_pk_bf16_f32 v69, v74, v75
	v_cvt_pk_bf16_f32 v70, v76, v77
	v_cvt_pk_bf16_f32 v71, v78, v79
	s_waitcnt lgkmcnt(0)
; #define SBAR() __builtin_amdgcn_sched_barrier(0)
; #define ATT_DMA_K(t) do { const bf16_t* kg_ = Kh + (size_t)(t) * 64 * LDK; LAS unsigned char* sb_ = lds + ((t) & 3) * KBUF; \
;     _Pragma("unroll") for (int i_ = 0; i_ < NKP; ++i_) __builtin_amdgcn_global_load_lds((const unsigned*)(kg_ + kgo[i_]), (LAS unsigned*)(sb_ + (wid + 8 * i_) * 1024), 16, 0, 0); } while (0)
; #define ATT_DMA_V(t, vs) do { const bf16_t* vg_ = Vh + (size_t)(t) * 64 * LDV; LAS unsigned char* sb_ = lds + V_OFF + (vs) * SHM_V; \
;     _Pragma("unroll") for (int i_ = 0; i_ < 2; ++i_) __builtin_amdgcn_global_load_lds((const unsigned*)(vg_ + vgo[i_]), (LAS unsigned*)(sb_ + (2 * wid + i_) * 1024), 16, 0, 0); } while (0)
; #define ATT_SEG(t) do { if constexpr (MODE != 0) { if (((t) == tL && tL > 0) || (t) == tR) { const float f_ = (t) == tR ? fR : fL; l_reg *= f_; \
;     _Pragma("unroll") for (int d = 0; d < 4; ++d) _Pragma("unroll") for (int r = 0; r < 16; ++r) o[d][r] *= f_; } } } while (0)
; #define ATT_TOP(N) do { asm volatile("s_waitcnt vmcnt(%0)" :: "n"(N) : "memory"); __builtin_amdgcn_s_barrier(); asm volatile("" ::: "memory"); } while (0)
; DI void expsum(f32x16& p, float& l_reg, bf16x8& pa0, bf16x8& pa1) {
; #pragma unroll
;     for (int r = 0; r < 16; ++r) p[r] = __builtin_amdgcn_exp2f(p[r]);
;     float ps = 0.f;
; #pragma unroll
;     for (int r = 0; r < 16; ++r) ps += p[r];
;     l_reg += ps; asm volatile("" : "+v"(l_reg));
;     ...
;     ATT_PK4(p, 0, pa0); ATT_PK4(p, 8, pa1);
;     ...
; }
; template <int DQK, int MODE, int LDQ, int LDK, int LDV> ...
;     ...
;     f32x16 pA, pB; bf16x8 pa0, pa1;
;     int v0 = 0, v1 = 1, v2 = 2;
;     ATT_TOP(NKP + 2);
;     { bf16x8 kf[NDA]; k_reads<DQK, 0, NDA>(kf, lds, 0, r32, hi); ATT_LGKM0(); qk_mma<0, NDA>(pA, kf, qr);
;       if constexpr (ND0 > NDA) { bf16x8 kg[ND0 - NDA]; k_reads<DQK, NDA, ND0>(kg, lds, 0, r32, hi); ATT_LGKM0(); qk_mma<NDA, ND0>(pA, kg, qr); }
;       ATT_BIAS(pA, 0, 0); }
;     if (wid >= 4) __builtin_amdgcn_s_setprio(1);
;     for (int j = 0; j < NT; ++j) {
;         if (j + 2 < NT) ATT_TOP(NKP + 2); else ATT_TOP(0);
;         if (j + 3 < NT) ATT_DMA_K(j + 3);
;         if (j + 2 < NT) ATT_DMA_V(j + 2, v2);
;         ATT_SEG(j); SBAR();
;         ATT_STEP(pA, pB, 0, v0, true, 1, j);
;         ATT_STEP(pB, pA, 1, v0, (j + 1 < NT), 0, j + 1);
;         { const int t_ = v0; v0 = v1; v1 = v2; v2 = t_; }
;     }
	ds_read_b128 v[230:233], v252 offset:12416
	ds_read_b128 v[234:237], v253 offset:12416
	ds_read_b128 v[238:241], v250 offset:12544
	ds_read_b128 v[242:245], v251 offset:12544
	ds_read_b128 v[246:249], v252 offset:12544
	ds_read_b128 v[250:253], v253 offset:12544
	s_setprio 1
	v_mfma_f32_32x32x16_bf16 v[48:63], v[64:67], v[198:201], v[48:63]
	v_mfma_f32_32x32x16_bf16 v[32:47], v[64:67], v[206:209], v[32:47]
	v_mfma_f32_32x32x16_bf16 v[16:31], v[64:67], v[214:217], v[16:31]
	v_mfma_f32_32x32x16_bf16 v[0:15], v[64:67], v[222:225], v[0:15]
	v_mfma_f32_32x32x16_bf16 v[48:63], v[68:71], v[202:205], v[48:63]
	v_mfma_f32_32x32x16_bf16 v[32:47], v[68:71], v[210:213], v[32:47]
	v_mfma_f32_32x32x16_bf16 v[16:31], v[68:71], v[218:221], v[16:31]
	v_mfma_f32_32x32x16_bf16 v[0:15], v[68:71], v[226:229], v[0:15]
	s_waitcnt lgkmcnt(0)
	v_mfma_f32_32x32x16_bf16 v[64:79], v[174:177], v[80:83], 0
	v_mfma_f32_32x32x16_bf16 v[64:79], v[178:181], v[84:87], v[64:79]
	v_mfma_f32_32x32x16_bf16 v[64:79], v[182:185], v[88:91], v[64:79]
	v_mfma_f32_32x32x16_bf16 v[64:79], v[186:189], v[92:95], v[64:79]
	v_mfma_f32_32x32x16_bf16 v[64:79], v[190:193], v[96:99], v[64:79]
	v_mfma_f32_32x32x16_bf16 v[64:79], v[194:197], v[100:103], v[64:79]
	v_mfma_f32_32x32x16_bf16 v[64:79], v[230:233], v[104:107], v[64:79]
	v_mfma_f32_32x32x16_bf16 v[64:79], v[234:237], v[108:111], v[64:79]
	v_mfma_f32_32x32x16_bf16 v[64:79], v[238:241], v[112:115], v[64:79]
	v_mfma_f32_32x32x16_bf16 v[64:79], v[242:245], v[116:119], v[64:79]
	v_mfma_f32_32x32x16_bf16 v[64:79], v[246:249], v[120:123], v[64:79]
	v_mfma_f32_32x32x16_bf16 v[64:79], v[250:253], v[124:127], v[64:79]
	s_setprio 0
	s_add_i32 s4, s43, -2
	s_and_b32 s4, s4, 3
	s_mulk_i32 s4, 0x6000
	v_add_u32_e32 v246, s4, v158
	v_add_u32_e32 v250, v246, v151
	v_add_u32_e32 v251, v246, v149
	v_add_u32_e32 v252, v246, v148
	v_add_u32_e32 v253, v246, v147
	ds_read_b128 v[190:193], v250 offset:128
	ds_read_b128 v[194:197], v251 offset:128
	ds_read_b128 v[174:177], v250
	ds_read_b128 v[178:181], v251
	ds_read_b128 v[182:185], v252
	ds_read_b128 v[186:189], v253
	ds_read_b64_tr_b16 v[198:199], v254 offset:0x2000
	ds_read_b64_tr_b16 v[200:201], v254 offset:0x2800
	ds_read_b64_tr_b16 v[202:203], v254 offset:0x3000
	ds_read_b64_tr_b16 v[204:205], v254 offset:0x3800
	ds_read_b64_tr_b16 v[206:207], v254 offset:0x2200
	ds_read_b64_tr_b16 v[208:209], v254 offset:0x2a00
	ds_read_b64_tr_b16 v[210:211], v254 offset:0x3200
	ds_read_b64_tr_b16 v[212:213], v254 offset:0x3a00
	ds_read_b64_tr_b16 v[214:215], v254 offset:0x2400
	ds_read_b64_tr_b16 v[216:217], v254 offset:0x2c00
	ds_read_b64_tr_b16 v[218:219], v254 offset:0x3400
	ds_read_b64_tr_b16 v[220:221], v254 offset:0x3c00
	ds_read_b64_tr_b16 v[222:223], v254 offset:0x2600
	ds_read_b64_tr_b16 v[224:225], v254 offset:0x2e00
	ds_read_b64_tr_b16 v[226:227], v254 offset:0x3600
	ds_read_b64_tr_b16 v[228:229], v254 offset:0x3e00
	s_setprio 2
	v_exp_f32_e32 v64, v64
	v_exp_f32_e32 v65, v65
	v_exp_f32_e32 v66, v66
	v_exp_f32_e32 v67, v67
	v_exp_f32_e32 v68, v68
	v_exp_f32_e32 v69, v69
	v_add_f32_e32 v230, v65, v64
	v_exp_f32_e32 v70, v70
	v_add_f32_e32 v230, v66, v230
	v_exp_f32_e32 v71, v71
	v_add_f32_e32 v230, v67, v230
	v_exp_f32_e32 v72, v72
	v_add_f32_e32 v230, v68, v230
	v_exp_f32_e32 v73, v73
	v_add_f32_e32 v230, v69, v230
	v_exp_f32_e32 v74, v74
	v_add_f32_e32 v230, v70, v230
	v_exp_f32_e32 v75, v75
	v_add_f32_e32 v230, v71, v230
	v_exp_f32_e32 v76, v76
	v_add_f32_e32 v230, v72, v230
	v_exp_f32_e32 v77, v77
	v_add_f32_e32 v230, v73, v230
	v_exp_f32_e32 v78, v78
	v_add_f32_e32 v230, v74, v230
	v_exp_f32_e32 v79, v79
	v_add_f32_e32 v230, v75, v230
	v_cvt_pk_bf16_f32 v64, v64, v65
	v_add_f32_e32 v230, v76, v230
	v_cvt_pk_bf16_f32 v65, v66, v67
	v_add_f32_e32 v230, v77, v230
	v_cvt_pk_bf16_f32 v66, v68, v69
	v_add_f32_e32 v230, v78, v230
	v_cvt_pk_bf16_f32 v67, v70, v71
	v_add_f32_e32 v230, v79, v230
	v_cvt_pk_bf16_f32 v68, v72, v73
	v_add_f32_e32 v173, v173, v230
	v_cvt_pk_bf16_f32 v69, v74, v75
	v_cvt_pk_bf16_f32 v70, v76, v77
	v_cvt_pk_bf16_f32 v71, v78, v79
	s_waitcnt lgkmcnt(0)
	ds_read_b128 v[230:233], v252 offset:128
	ds_read_b128 v[234:237], v253 offset:128
	ds_read_b128 v[238:241], v250 offset:256
	ds_read_b128 v[242:245], v251 offset:256
	ds_read_b128 v[246:249], v252 offset:256
	ds_read_b128 v[250:253], v253 offset:256
	s_setprio 1
	v_mfma_f32_32x32x16_bf16 v[48:63], v[64:67], v[198:201], v[48:63]
	v_mfma_f32_32x32x16_bf16 v[32:47], v[64:67], v[206:209], v[32:47]
	v_mfma_f32_32x32x16_bf16 v[16:31], v[64:67], v[214:217], v[16:31]
	v_mfma_f32_32x32x16_bf16 v[0:15], v[64:67], v[222:225], v[0:15]
	v_mfma_f32_32x32x16_bf16 v[48:63], v[68:71], v[202:205], v[48:63]
	v_mfma_f32_32x32x16_bf16 v[32:47], v[68:71], v[210:213], v[32:47]
	v_mfma_f32_32x32x16_bf16 v[16:31], v[68:71], v[218:221], v[16:31]
	v_mfma_f32_32x32x16_bf16 v[0:15], v[68:71], v[226:229], v[0:15]
	s_waitcnt lgkmcnt(0)
	v_mfma_f32_32x32x16_bf16 v[64:79], v[174:177], v[80:83], 0
	v_mfma_f32_32x32x16_bf16 v[64:79], v[178:181], v[84:87], v[64:79]
	v_mfma_f32_32x32x16_bf16 v[64:79], v[182:185], v[88:91], v[64:79]
	v_mfma_f32_32x32x16_bf16 v[64:79], v[186:189], v[92:95], v[64:79]
	v_mfma_f32_32x32x16_bf16 v[64:79], v[190:193], v[96:99], v[64:79]
	v_mfma_f32_32x32x16_bf16 v[64:79], v[194:197], v[100:103], v[64:79]
	v_mfma_f32_32x32x16_bf16 v[64:79], v[230:233], v[104:107], v[64:79]
	v_mfma_f32_32x32x16_bf16 v[64:79], v[234:237], v[108:111], v[64:79]
	v_mfma_f32_32x32x16_bf16 v[64:79], v[238:241], v[112:115], v[64:79]
	v_mfma_f32_32x32x16_bf16 v[64:79], v[242:245], v[116:119], v[64:79]
	v_mfma_f32_32x32x16_bf16 v[64:79], v[246:249], v[120:123], v[64:79]
	v_mfma_f32_32x32x16_bf16 v[64:79], v[250:253], v[124:127], v[64:79]
	s_add_i32 s43, s43, 1
	v_add_u32_e32 v136, s36, v136
	v_add_u32_e32 v138, s36, v138
	v_add_u32_e32 v140, s36, v140
	v_add_u32_e32 v142, s38, v142
	v_add_u32_e32 v144, s38, v144
	s_cmp_eq_u32 s43, 64
	s_mov_b32 s4, s0
	s_cbranch_scc0 .LBB0_1982
